# plus_wconv_second_group_l2_prefetch
# speedup vs baseline: 1.0059x; 1.0059x over previous
; __device__ __forceinline__ void wconv(unsigned char* lds, const float* __restrict__ src, bf16_t* __restrict__ dst, int K, int Nsrc, int Ndst, int mode, int nbatch) {
;     ...
;     __syncthreads();
; #pragma unroll
;     for (int i = 0; i < 8; ++i) {
;       const int kk = (tid >> 6) + 8 * i;
;       float v = 0.f; if (scol >= 0) v = s[(size_t)(kt * 64 + kk) * Nsrc + scol] * scale;
;       tile[kk * 65 + nn] = v;
;     }
.LBB0_33:
	s_or_saveexec_b64 s[6:7], s[2:3]
	s_lshl_b32 s2, s16, 6
	v_lshl_add_u64 v[8:9], v[2:3], 2, s[8:9]
	v_mov_b32_e32 v10, 0
	v_mov_b32_e32 v11, 0
	s_xor_b64 exec, exec, s[6:7]
	s_cbranch_execz .LBB0_35
	v_add_u32_e32 v2, s2, v7
	v_mad_i64_i32 v[10:11], s[8:9], v2, s13, v[8:9]
	v_add_u32_e32 v21, 8, v2
	v_mad_i64_i32 v[22:23], s[8:9], v21, s13, v[8:9]
	global_load_dword v21, v[10:11], off
	global_load_dword v26, v[22:23], off
	v_add_u32_e32 v10, 16, v2
	v_mad_i64_i32 v[10:11], s[8:9], v10, s13, v[8:9]
	v_add_u32_e32 v2, 24, v2
	v_mad_i64_i32 v[22:23], s[8:9], v2, s13, v[8:9]
	global_load_dword v24, v[10:11], off
	global_load_dword v25, v[22:23], off
	v_add_u32_e32 v40, s2, v13
	v_mad_i64_i32 v[42:43], s[8:9], v40, s13, v[8:9]
	v_add_u32_e32 v40, s2, v14
	v_mad_i64_i32 v[44:45], s[8:9], v40, s13, v[8:9]
	global_load_dword v46, v[42:43], off
	global_load_dword v47, v[44:45], off
	v_add_u32_e32 v42, s2, v15
	v_mad_i64_i32 v[42:43], s[8:9], v42, s13, v[8:9]
	v_add_u32_e32 v44, s2, v16
	v_mad_i64_i32 v[48:49], s[8:9], v44, s13, v[8:9]
	global_load_dword v50, v[42:43], off
	global_load_dword v51, v[48:49], off
	s_waitcnt vmcnt(7)
	v_mul_f32_e32 v2, v6, v21
	s_waitcnt vmcnt(6)
	v_mul_f32_e32 v10, v6, v26
	ds_write_b32 v17, v2
	ds_write_b32 v17, v10 offset:2080
	s_waitcnt vmcnt(4)
	v_pk_mul_f32 v[10:11], v[6:7], v[24:25] op_sel_hi:[0,1]

; __device__ __forceinline__ void wconv(unsigned char* lds, const float* __restrict__ src, bf16_t* __restrict__ dst, int K, int Nsrc, int Ndst, int mode, int nbatch) {
;     ...
;     __syncthreads();
; #pragma unroll
;     for (int i = 0; i < 8; ++i) {
;       const int kk = (tid >> 6) + 8 * i;
;       float v = 0.f; if (scol >= 0) v = s[(size_t)(kt * 64 + kk) * Nsrc + scol] * scale;
;       tile[kk * 65 + nn] = v;
;     }
.LBB0_44:
	s_or_saveexec_b64 s[8:9], s[2:3]
	s_lshl_b32 s2, s17, 6
	v_lshl_add_u64 v[6:7], v[2:3], 2, s[10:11]
	v_mov_b32_e32 v2, 0
	v_mov_b32_e32 v17, 0
	s_xor_b64 exec, exec, s[8:9]
	s_cbranch_execz .LBB0_46
	v_add_u32_e32 v18, s2, v8
	v_ashrrev_i32_e32 v19, 31, v18
	v_lshlrev_b64 v[20:21], 12, v[18:19]
	v_add_u32_e32 v22, 8, v18
	v_add_u32_e32 v24, 16, v18
	v_add_u32_e32 v18, 24, v18
	v_ashrrev_i32_e32 v23, 31, v22
	v_ashrrev_i32_e32 v25, 31, v24
	v_ashrrev_i32_e32 v19, 31, v18
	v_lshl_add_u64 v[20:21], v[6:7], 0, v[20:21]
	v_lshlrev_b64 v[22:23], 12, v[22:23]
	v_lshlrev_b64 v[24:25], 12, v[24:25]
	v_lshlrev_b64 v[18:19], 12, v[18:19]
	v_lshl_add_u64 v[22:23], v[6:7], 0, v[22:23]
	v_lshl_add_u64 v[24:25], v[6:7], 0, v[24:25]
	v_lshl_add_u64 v[18:19], v[6:7], 0, v[18:19]
	global_load_dword v20, v[20:21], off
	s_nop 0
	global_load_dword v21, v[22:23], off
	global_load_dword v2, v[24:25], off
	global_load_dword v17, v[18:19], off
	v_add_u32_e32 v40, s2, v10
	v_ashrrev_i32_e32 v41, 31, v40
	v_add_u32_e32 v42, s2, v11
	v_add_u32_e32 v44, s2, v12
	v_add_u32_e32 v46, s2, v13
	v_lshlrev_b64 v[40:41], 12, v[40:41]
	v_ashrrev_i32_e32 v43, 31, v42
	v_ashrrev_i32_e32 v45, 31, v44
	v_ashrrev_i32_e32 v47, 31, v46
	v_lshl_add_u64 v[40:41], v[6:7], 0, v[40:41]
	v_lshlrev_b64 v[42:43], 12, v[42:43]
	v_lshlrev_b64 v[44:45], 12, v[44:45]
	v_lshlrev_b64 v[46:47], 12, v[46:47]
	v_lshl_add_u64 v[42:43], v[6:7], 0, v[42:43]
	v_lshl_add_u64 v[44:45], v[6:7], 0, v[44:45]
	v_lshl_add_u64 v[48:49], v[6:7], 0, v[46:47]
	global_load_dword v50, v[40:41], off
	s_nop 0
	global_load_dword v51, v[42:43], off
	global_load_dword v52, v[44:45], off
	global_load_dword v53, v[48:49], off
	s_waitcnt vmcnt(7)
	ds_write_b32 v14, v20
	s_waitcnt vmcnt(6)
	ds_write_b32 v14, v21 offset:2080
.LBB0_46:
	s_or_b64 exec, exec, s[8:9]
	s_waitcnt vmcnt(5)
	ds_write_b32 v14, v2 offset:4160
	s_waitcnt vmcnt(4)
	ds_write_b32 v14, v17 offset:6240
	s_and_saveexec_b64 s[8:9], vcc
	s_xor_b64 s[8:9], exec, s[8:9]
	s_cbranch_execz .LBB0_48
	ds_write_b32 v14, v3 offset:8320
	ds_write_b32 v14, v3 offset:10400

; __device__ __forceinline__ void wconv(unsigned char* lds, const float* __restrict__ src, bf16_t* __restrict__ dst, int K, int Nsrc, int Ndst, int mode, int nbatch) {
;     ...
;     __syncthreads();
; #pragma unroll
;     for (int i = 0; i < 8; ++i) {
;       const int kk = (tid >> 6) + 8 * i;
;       float v = 0.f; if (scol >= 0) v = s[(size_t)(kt * 64 + kk) * Nsrc + scol] * scale;
;       tile[kk * 65 + nn] = v;
;     }
.LBB0_55:
	s_or_saveexec_b64 s[8:9], s[2:3]
	s_and_b32 s2, s17, 0xffffffc0
	v_lshl_add_u64 v[6:7], v[2:3], 2, s[10:11]
	v_mov_b32_e32 v2, 0
	v_mov_b32_e32 v17, 0
	s_xor_b64 exec, exec, s[8:9]
	s_cbranch_execz .LBB0_57
	v_add_u32_e32 v18, s2, v8
	v_ashrrev_i32_e32 v19, 31, v18
	v_lshlrev_b64 v[20:21], 14, v[18:19]
	v_add_u32_e32 v22, 8, v18
	v_add_u32_e32 v24, 16, v18
	v_add_u32_e32 v18, 24, v18
	v_ashrrev_i32_e32 v23, 31, v22
	v_ashrrev_i32_e32 v25, 31, v24
	v_ashrrev_i32_e32 v19, 31, v18
	v_lshl_add_u64 v[20:21], v[6:7], 0, v[20:21]
	v_lshlrev_b64 v[22:23], 14, v[22:23]
	v_lshlrev_b64 v[24:25], 14, v[24:25]
	v_lshlrev_b64 v[18:19], 14, v[18:19]
	v_lshl_add_u64 v[22:23], v[6:7], 0, v[22:23]
	v_lshl_add_u64 v[24:25], v[6:7], 0, v[24:25]
	v_lshl_add_u64 v[18:19], v[6:7], 0, v[18:19]
	global_load_dword v20, v[20:21], off
	s_nop 0
	global_load_dword v21, v[22:23], off
	global_load_dword v2, v[24:25], off
	global_load_dword v17, v[18:19], off
	v_add_u32_e32 v40, s2, v10
	v_ashrrev_i32_e32 v41, 31, v40
	v_add_u32_e32 v42, s2, v11
	v_add_u32_e32 v44, s2, v12
	v_add_u32_e32 v46, s2, v13
	v_lshlrev_b64 v[40:41], 14, v[40:41]
	v_ashrrev_i32_e32 v43, 31, v42
	v_ashrrev_i32_e32 v45, 31, v44
	v_ashrrev_i32_e32 v47, 31, v46
	v_lshl_add_u64 v[40:41], v[6:7], 0, v[40:41]
	v_lshlrev_b64 v[42:43], 14, v[42:43]
	v_lshlrev_b64 v[44:45], 14, v[44:45]
	v_lshlrev_b64 v[46:47], 14, v[46:47]
	v_lshl_add_u64 v[42:43], v[6:7], 0, v[42:43]
	v_lshl_add_u64 v[44:45], v[6:7], 0, v[44:45]
	v_lshl_add_u64 v[48:49], v[6:7], 0, v[46:47]
	global_load_dword v50, v[40:41], off
	s_nop 0
	global_load_dword v51, v[42:43], off
	global_load_dword v52, v[44:45], off
	global_load_dword v53, v[48:49], off
	s_waitcnt vmcnt(7)
	ds_write_b32 v14, v20
	s_waitcnt vmcnt(6)
	ds_write_b32 v14, v21 offset:2080

; __device__ __forceinline__ void wconv(unsigned char* lds, const float* __restrict__ src, bf16_t* __restrict__ dst, int K, int Nsrc, int Ndst, int mode, int nbatch) {
;     ...
;     __syncthreads();
; #pragma unroll
;     for (int i = 0; i < 8; ++i) {
;       const int kk = (tid >> 6) + 8 * i;
;       float v = 0.f; if (scol >= 0) v = s[(size_t)(kt * 64 + kk) * Nsrc + scol] * scale;
;       tile[kk * 65 + nn] = v;
;     }
.LBB0_77:
	s_or_saveexec_b64 s[2:3], s[0:1]
	s_lshl_b32 s0, s13, 6
	v_lshl_add_u64 v[6:7], v[2:3], 2, s[6:7]
	v_mov_b32_e32 v2, 0
	v_mov_b32_e32 v17, 0
	s_xor_b64 exec, exec, s[2:3]
	s_cbranch_execz .LBB0_79
	v_add_u32_e32 v2, s0, v8
	v_add_u32_e32 v17, 8, v2
	v_mad_i64_i32 v[18:19], s[6:7], v2, s10, v[6:7]
	v_mad_i64_i32 v[20:21], s[6:7], v17, s10, v[6:7]
	v_add_u32_e32 v17, 16, v2
	v_add_u32_e32 v2, 24, v2
	v_mad_i64_i32 v[22:23], s[6:7], v17, s10, v[6:7]
	v_mad_i64_i32 v[24:25], s[6:7], v2, s10, v[6:7]
	global_load_dword v18, v[18:19], off
	s_nop 0
	global_load_dword v19, v[20:21], off
	global_load_dword v2, v[22:23], off
	global_load_dword v17, v[24:25], off
	v_add_u32_e32 v40, s0, v10
	v_mad_i64_i32 v[42:43], s[6:7], v40, s10, v[6:7]
	v_add_u32_e32 v40, s0, v11
	v_mad_i64_i32 v[44:45], s[6:7], v40, s10, v[6:7]
	v_add_u32_e32 v40, s0, v12
	v_mad_i64_i32 v[46:47], s[6:7], v40, s10, v[6:7]
	v_add_u32_e32 v40, s0, v13
	v_mad_i64_i32 v[48:49], s[6:7], v40, s10, v[6:7]
	global_load_dword v50, v[42:43], off
	s_nop 0
	global_load_dword v51, v[44:45], off
	global_load_dword v52, v[46:47], off
	global_load_dword v53, v[48:49], off
	s_waitcnt vmcnt(7)
	ds_write_b32 v14, v18
	s_waitcnt vmcnt(6)
	ds_write_b32 v14, v19 offset:2080
.LBB0_79:
	s_or_b64 exec, exec, s[2:3]
	s_waitcnt vmcnt(5)
	ds_write_b32 v14, v2 offset:4160
	s_waitcnt vmcnt(4)
	ds_write_b32 v14, v17 offset:6240
	s_and_saveexec_b64 s[2:3], vcc
	s_xor_b64 s[2:3], exec, s[2:3]
	s_cbranch_execz .LBB0_81
	ds_write_b32 v14, v3 offset:8320
	ds_write_b32 v14, v3 offset:10400

; __device__ __forceinline__ void wconv(unsigned char* lds, const float* __restrict__ src, bf16_t* __restrict__ dst, int K, int Nsrc, int Ndst, int mode, int nbatch) {
;     ...
;     __syncthreads();
; #pragma unroll
;     for (int i = 0; i < 8; ++i) {
;       const int kk = (tid >> 6) + 8 * i;
;       float v = 0.f; if (scol >= 0) v = s[(size_t)(kt * 64 + kk) * Nsrc + scol] * scale;
;       tile[kk * 65 + nn] = v;
;     }
.LBB0_88:
	s_or_saveexec_b64 s[6:7], s[0:1]
	s_lshl_b32 s0, s14, 6
	v_lshl_add_u64 v[6:7], v[2:3], 2, s[8:9]
	v_mov_b32_e32 v2, 0
	v_mov_b32_e32 v17, 0
	s_xor_b64 exec, exec, s[6:7]
	s_cbranch_execz .LBB0_90
	v_add_u32_e32 v2, s0, v8
	v_add_u32_e32 v17, 8, v2
	v_mad_i64_i32 v[18:19], s[8:9], v2, s12, v[6:7]
	v_mad_i64_i32 v[20:21], s[8:9], v17, s12, v[6:7]
	v_add_u32_e32 v17, 16, v2
	v_add_u32_e32 v2, 24, v2
	v_mad_i64_i32 v[22:23], s[8:9], v17, s12, v[6:7]
	v_mad_i64_i32 v[24:25], s[8:9], v2, s12, v[6:7]
	global_load_dword v18, v[18:19], off
	s_nop 0
	global_load_dword v19, v[20:21], off
	global_load_dword v2, v[22:23], off
	global_load_dword v17, v[24:25], off
	v_add_u32_e32 v40, s0, v10
	v_mad_i64_i32 v[42:43], s[8:9], v40, s12, v[6:7]
	v_add_u32_e32 v40, s0, v11
	v_mad_i64_i32 v[44:45], s[8:9], v40, s12, v[6:7]
	v_add_u32_e32 v40, s0, v12
	v_mad_i64_i32 v[46:47], s[8:9], v40, s12, v[6:7]
	v_add_u32_e32 v40, s0, v13
	v_mad_i64_i32 v[48:49], s[8:9], v40, s12, v[6:7]
	global_load_dword v50, v[42:43], off
	s_nop 0
	global_load_dword v51, v[44:45], off
	global_load_dword v52, v[46:47], off
	global_load_dword v53, v[48:49], off
	s_waitcnt vmcnt(7)
	ds_write_b32 v14, v18
	s_waitcnt vmcnt(6)
	ds_write_b32 v14, v19 offset:2080
.LBB0_90:
	s_or_b64 exec, exec, s[6:7]
	s_waitcnt vmcnt(5)
	ds_write_b32 v14, v2 offset:4160
	s_waitcnt vmcnt(4)
	ds_write_b32 v14, v17 offset:6240
	s_and_saveexec_b64 s[6:7], vcc
	s_xor_b64 s[6:7], exec, s[6:7]
	s_cbranch_execz .LBB0_92
	ds_write_b32 v14, v3 offset:8320
	ds_write_b32 v14, v3 offset:10400

; __device__ __forceinline__ void wconv(unsigned char* lds, const float* __restrict__ src, bf16_t* __restrict__ dst, int K, int Nsrc, int Ndst, int mode, int nbatch) {
;     ...
;     __syncthreads();
; #pragma unroll
;     for (int i = 0; i < 8; ++i) {
;       const int kk = (tid >> 6) + 8 * i;
;       float v = 0.f; if (scol >= 0) v = s[(size_t)(kt * 64 + kk) * Nsrc + scol] * scale;
;       tile[kk * 65 + nn] = v;
;     }
.LBB0_99:
	s_or_saveexec_b64 s[6:7], s[0:1]
	s_lshl_b32 s0, s15, 6
	v_lshl_add_u64 v[6:7], v[2:3], 2, s[8:9]
	v_mov_b32_e32 v2, 0
	v_mov_b32_e32 v17, 0
	s_xor_b64 exec, exec, s[6:7]
	s_cbranch_execz .LBB0_101
	v_add_u32_e32 v18, s0, v8
	v_ashrrev_i32_e32 v19, 31, v18
	v_lshlrev_b64 v[20:21], 12, v[18:19]
	v_add_u32_e32 v22, 8, v18
	v_add_u32_e32 v24, 16, v18
	v_add_u32_e32 v18, 24, v18
	v_ashrrev_i32_e32 v23, 31, v22
	v_ashrrev_i32_e32 v25, 31, v24
	v_ashrrev_i32_e32 v19, 31, v18
	v_lshl_add_u64 v[20:21], v[6:7], 0, v[20:21]
	v_lshlrev_b64 v[22:23], 12, v[22:23]
	v_lshlrev_b64 v[24:25], 12, v[24:25]
	v_lshlrev_b64 v[18:19], 12, v[18:19]
	v_lshl_add_u64 v[22:23], v[6:7], 0, v[22:23]
	v_lshl_add_u64 v[24:25], v[6:7], 0, v[24:25]
	v_lshl_add_u64 v[18:19], v[6:7], 0, v[18:19]
	global_load_dword v20, v[20:21], off
	s_nop 0
	global_load_dword v21, v[22:23], off
	global_load_dword v2, v[24:25], off
	global_load_dword v17, v[18:19], off
	v_add_u32_e32 v40, s0, v10
	v_ashrrev_i32_e32 v41, 31, v40
	v_add_u32_e32 v42, s0, v11
	v_add_u32_e32 v44, s0, v12
	v_add_u32_e32 v46, s0, v13
	v_lshlrev_b64 v[40:41], 12, v[40:41]
	v_ashrrev_i32_e32 v43, 31, v42
	v_ashrrev_i32_e32 v45, 31, v44
	v_ashrrev_i32_e32 v47, 31, v46
	v_lshl_add_u64 v[40:41], v[6:7], 0, v[40:41]
	v_lshlrev_b64 v[42:43], 12, v[42:43]
	v_lshlrev_b64 v[44:45], 12, v[44:45]
	v_lshlrev_b64 v[46:47], 12, v[46:47]
	v_lshl_add_u64 v[42:43], v[6:7], 0, v[42:43]
	v_lshl_add_u64 v[44:45], v[6:7], 0, v[44:45]
	v_lshl_add_u64 v[48:49], v[6:7], 0, v[46:47]
	global_load_dword v50, v[40:41], off
	s_nop 0
	global_load_dword v51, v[42:43], off
	global_load_dword v52, v[44:45], off
	global_load_dword v53, v[48:49], off
	s_waitcnt vmcnt(7)
	ds_write_b32 v14, v20
	s_waitcnt vmcnt(6)
	ds_write_b32 v14, v21 offset:2080

; __device__ __forceinline__ void wconv(unsigned char* lds, const float* __restrict__ src, bf16_t* __restrict__ dst, int K, int Nsrc, int Ndst, int mode, int nbatch) {
;     ...
;     __syncthreads();
; #pragma unroll
;     for (int i = 0; i < 8; ++i) {
;       const int kk = (tid >> 6) + 8 * i;
;       float v = 0.f; if (scol >= 0) v = s[(size_t)(kt * 64 + kk) * Nsrc + scol] * scale;
;       tile[kk * 65 + nn] = v;
;     }
.LBB0_121:
	s_or_saveexec_b64 s[6:7], s[0:1]
	s_lshl_b32 s0, s15, 6
	v_lshl_add_u64 v[6:7], v[2:3], 2, s[8:9]
	v_mov_b32_e32 v2, 0
	v_mov_b32_e32 v17, 0
	s_xor_b64 exec, exec, s[6:7]
	s_cbranch_execz .LBB0_123
	v_add_u32_e32 v18, s0, v8
	v_ashrrev_i32_e32 v19, 31, v18
	v_lshlrev_b64 v[20:21], 9, v[18:19]
	v_add_u32_e32 v22, 8, v18
	v_add_u32_e32 v24, 16, v18
	v_add_u32_e32 v18, 24, v18
	v_ashrrev_i32_e32 v23, 31, v22
	v_ashrrev_i32_e32 v25, 31, v24
	v_ashrrev_i32_e32 v19, 31, v18
	v_lshl_add_u64 v[20:21], v[6:7], 0, v[20:21]
	v_lshlrev_b64 v[22:23], 9, v[22:23]
	v_lshlrev_b64 v[24:25], 9, v[24:25]
	v_lshlrev_b64 v[18:19], 9, v[18:19]
	v_lshl_add_u64 v[22:23], v[6:7], 0, v[22:23]
	v_lshl_add_u64 v[24:25], v[6:7], 0, v[24:25]
	v_lshl_add_u64 v[18:19], v[6:7], 0, v[18:19]
	global_load_dword v20, v[20:21], off
	s_nop 0
	global_load_dword v21, v[22:23], off
	global_load_dword v2, v[24:25], off
	global_load_dword v17, v[18:19], off
	v_add_u32_e32 v40, s0, v10
	v_ashrrev_i32_e32 v41, 31, v40
	v_add_u32_e32 v42, s0, v11
	v_add_u32_e32 v44, s0, v12
	v_add_u32_e32 v46, s0, v13
	v_lshlrev_b64 v[40:41], 9, v[40:41]
	v_ashrrev_i32_e32 v43, 31, v42
	v_ashrrev_i32_e32 v45, 31, v44
	v_ashrrev_i32_e32 v47, 31, v46
	v_lshl_add_u64 v[40:41], v[6:7], 0, v[40:41]
	v_lshlrev_b64 v[42:43], 9, v[42:43]
	v_lshlrev_b64 v[44:45], 9, v[44:45]
	v_lshlrev_b64 v[46:47], 9, v[46:47]
	v_lshl_add_u64 v[42:43], v[6:7], 0, v[42:43]
	v_lshl_add_u64 v[44:45], v[6:7], 0, v[44:45]
	v_lshl_add_u64 v[48:49], v[6:7], 0, v[46:47]
	global_load_dword v50, v[40:41], off
	s_nop 0
	global_load_dword v51, v[42:43], off
	global_load_dword v52, v[44:45], off
	global_load_dword v53, v[48:49], off
	s_waitcnt vmcnt(7)
	ds_write_b32 v14, v20
	s_waitcnt vmcnt(6)
	ds_write_b32 v14, v21 offset:2080
